# ssd_pass2 per-head epilogue: four z-gate loads issued together (extra three into dead P-fragment registers), counted vmcnt instead of load-wait per load
# speedup vs baseline: 1.0023x; 1.0023x over previous
; __device__ __forceinline__ float bflo(unsigned u) { return __uint_as_float(u << 16); }
; __device__ __forceinline__ float bfhi(unsigned u) { return __uint_as_float(u & 0xFFFF0000u); }
; __device__ __forceinline__ float siluf_(float x) { return x * __builtin_amdgcn_rcpf(1.f + __expf(-x)); }
; __device__ __forceinline__ f32x16 mfma32(bf16x8 a, bf16x8 b, f32x16 c) { return __builtin_amdgcn_mfma_f32_32x32x16_bf16(a, b, c, 0, 0, 0); }
; __device__ __forceinline__ void ssd_pass2(const Params& p, int layer, int task, char* sm) {
;     ...
;     for (int ks = 0; ks < nks; ks++) {
;       bf16x8 xf = *(const bf16x8*)(sXT + (32 * wc2 + r32) * 136 + ks * 16 + 8 * h5);
;       bf16x8 mf = *(const bf16x8*)(sM + (32 * wr + r32) * 136 + ks * 16 + 8 * h5);
;       yd = mfma32(xf, mf, yd);
;     }
;     {
; #pragma unroll
;       for (int ks = 0; ks < 8; ks++) {
;         bf16x8 cf = *(const bf16x8*)(sC + (32 * wr + r32) * 136 + ks * 16 + 8 * h5);
;         yo = mfma32(pfr[ks], cf, yo);
;       }
;     }
;     {
;       const int lp = 32 * wr + r32; const int l = 64 * lh + lp; const size_t tok = tok0 + l;
;       const float eo = __expf(sAcs[l * 8 + hh]);
;       float ss = 0.f;
; #pragma unroll
;       for (int q = 0; q < 4; q++) {
;         const int pp = 32 * wc2 + 8 * q + 4 * h5;
;         uint2 zz = *(const uint2*)(p.P + tok * PW + C_SSZ + hd * 64 + pp);
;         float v0 = (yd[4 * q] + eo * yo[4 * q]) * siluf_(bflo(zz.x));
;         float v1 = (yd[4 * q + 1] + eo * yo[4 * q + 1]) * siluf_(bfhi(zz.x));
;         float v2 = (yd[4 * q + 2] + eo * yo[4 * q + 2]) * siluf_(bflo(zz.y));
;         float v3 = (yd[4 * q + 3] + eo * yo[4 * q + 3]) * siluf_(bfhi(zz.y));
;         ss += v0 * v0 + v1 * v1 + v2 * v2 + v3 * v3;
;         *(uint2*)(p.Y + tok * YW + Y_SSD + hd * 64 + pp) = make_uint2(pk2(v0, v1), pk2(v2, v3));
;       }
.LBB0_1775:
	ds_read_b128 v[162:165], v144
	ds_read_b128 v[166:169], v160
	s_add_i32 s74, s74, 1
	v_add_u32_e32 v160, 32, v160
	s_cmp_ge_u32 s74, s85
	v_add_u32_e32 v144, 32, v144
	s_waitcnt lgkmcnt(0)
	v_mfma_f32_32x32x16_bf16 v[32:47], v[162:165], v[166:169], v[32:47]
	s_cbranch_scc0 .LBB0_1775
	v_cvt_pk_bf16_f32 v108, v108, v109
	v_cvt_pk_bf16_f32 v109, v110, v111
	v_cvt_pk_bf16_f32 v110, v100, v101
	v_cvt_pk_bf16_f32 v111, v102, v103
	v_cvt_pk_bf16_f32 v103, v94, v95
	v_cvt_pk_bf16_f32 v95, v86, v87
	v_cvt_pk_bf16_f32 v87, v78, v79
	v_cvt_pk_bf16_f32 v79, v70, v71
	v_cvt_pk_bf16_f32 v71, v62, v63
	v_cvt_pk_bf16_f32 v62, v52, v53
	v_cvt_pk_bf16_f32 v63, v54, v55
	v_cvt_pk_bf16_f32 v52, v56, v57
	v_cvt_pk_bf16_f32 v53, v58, v59
	v_cvt_pk_bf16_f32 v54, v48, v49
	v_cvt_pk_bf16_f32 v55, v50, v51
	ds_read_b128 v[48:51], v188 offset:8192
	ds_read_b128 v[56:59], v188 offset:8224
	s_waitcnt lgkmcnt(1)
	v_mfma_f32_32x32x16_bf16 v[16:31], v[108:111], v[48:51], v[16:31]
	v_cvt_pk_bf16_f32 v100, v104, v105
	v_cvt_pk_bf16_f32 v101, v106, v107
	v_cvt_pk_bf16_f32 v102, v92, v93
	v_cvt_pk_bf16_f32 v92, v96, v97
	v_cvt_pk_bf16_f32 v93, v98, v99
	v_cvt_pk_bf16_f32 v94, v84, v85
	ds_read_b128 v[48:51], v188 offset:8256
	s_waitcnt lgkmcnt(1)
	v_mfma_f32_32x32x16_bf16 v[16:31], v[100:103], v[56:59], v[16:31]
	v_cvt_pk_bf16_f32 v84, v88, v89
	v_cvt_pk_bf16_f32 v85, v90, v91
	v_cvt_pk_bf16_f32 v86, v76, v77
	v_cvt_pk_bf16_f32 v76, v80, v81
	v_cvt_pk_bf16_f32 v77, v82, v83
	v_cvt_pk_bf16_f32 v78, v68, v69
	v_cvt_pk_bf16_f32 v68, v72, v73
	s_waitcnt lgkmcnt(0)
	v_mfma_f32_32x32x16_bf16 v[16:31], v[92:95], v[48:51], v[16:31]
	ds_read_b128 v[48:51], v188 offset:8288
	v_cvt_pk_bf16_f32 v69, v74, v75
	v_cvt_pk_bf16_f32 v70, v60, v61
	v_cvt_pk_bf16_f32 v60, v64, v65
	v_cvt_pk_bf16_f32 v61, v66, v67
	s_lshl_b32 s68, s68, 1
	s_waitcnt lgkmcnt(0)
	v_mfma_f32_32x32x16_bf16 v[16:31], v[84:87], v[48:51], v[16:31]
	ds_read_b128 v[48:51], v188 offset:8320
	s_waitcnt lgkmcnt(0)
	v_mfma_f32_32x32x16_bf16 v[16:31], v[76:79], v[48:51], v[16:31]
	ds_read_b128 v[48:51], v188 offset:8352
	s_waitcnt lgkmcnt(0)
	v_mfma_f32_32x32x16_bf16 v[16:31], v[68:71], v[48:51], v[16:31]
	ds_read_b128 v[48:51], v188 offset:8384
	s_waitcnt lgkmcnt(0)
	v_mfma_f32_32x32x16_bf16 v[16:31], v[60:63], v[48:51], v[16:31]
	ds_read_b128 v[48:51], v188 offset:8416
	s_waitcnt lgkmcnt(0)
	v_mfma_f32_32x32x16_bf16 v[16:31], v[52:55], v[48:51], v[16:31]
	v_lshl_add_u64 v[50:51], v[156:157], 0, s[68:69]
	global_load_dwordx2 v[52:53], v[50:51], off
	global_load_dwordx2 v[60:61], v[50:51], off offset:16
	global_load_dwordx2 v[68:69], v[50:51], off offset:32
	global_load_dwordx2 v[76:77], v[50:51], off offset:48
	v_lshl_add_u32 v48, s78, 2, v246
	ds_read_b32 v48, v48
	s_waitcnt lgkmcnt(0)
	v_mul_f32_e32 v48, 0x3fb8aa3b, v48
	v_exp_f32_e32 v48, v48
	s_waitcnt vmcnt(3)
	v_lshlrev_b32_e32 v54, 16, v52
	v_mul_f32_e32 v49, 0xbfb8aa3b, v54
	v_exp_f32_e32 v49, v49
	v_and_b32_e32 v55, 0xffff0000, v52
	v_add_f32_e32 v49, 1.0, v49
	v_pk_fma_f32 v[16:17], v[16:17], v[48:49], v[32:33] op_sel_hi:[1,0,1]
	v_mul_f32_e32 v32, 0xbfb8aa3b, v55
	v_exp_f32_e32 v32, v32
	v_rcp_f32_e32 v56, v49
	v_add_f32_e32 v32, 1.0, v32
	v_rcp_f32_e32 v57, v32
	s_nop 0
	v_pk_mul_f32 v[32:33], v[56:57], v[54:55]
	s_nop 0
	v_pk_mul_f32 v[16:17], v[16:17], v[32:33]
	v_lshlrev_b32_e32 v32, 16, v53
	v_mul_f32_e32 v49, 0xbfb8aa3b, v32
	v_exp_f32_e32 v49, v49
	v_and_b32_e32 v33, 0xffff0000, v53
	v_add_f32_e32 v49, 1.0, v49
	v_pk_fma_f32 v[18:19], v[18:19], v[48:49], v[34:35] op_sel_hi:[1,0,1]
	v_mul_f32_e32 v34, 0xbfb8aa3b, v33
	v_exp_f32_e32 v34, v34
	v_rcp_f32_e32 v52, v49
	v_pk_fma_f32 v[20:21], v[20:21], v[48:49], v[36:37] op_sel_hi:[1,0,1]
	v_pk_fma_f32 v[22:23], v[22:23], v[48:49], v[38:39] op_sel_hi:[1,0,1]
	v_add_f32_e32 v34, 1.0, v34
	v_rcp_f32_e32 v53, v34
	v_cvt_pk_bf16_f32 v34, v16, v17
	v_pk_fma_f32 v[24:25], v[24:25], v[48:49], v[40:41] op_sel_hi:[1,0,1]
	v_pk_fma_f32 v[28:29], v[28:29], v[48:49], v[44:45] op_sel_hi:[1,0,1]
	v_pk_mul_f32 v[32:33], v[52:53], v[32:33]
	s_nop 0
	v_pk_mul_f32 v[18:19], v[18:19], v[32:33]
	v_lshl_add_u64 v[32:33], v[158:159], 0, s[68:69]
	v_cvt_pk_bf16_f32 v35, v18, v19
	global_store_dwordx2 v[32:33], v[34:35], off offset:2048
	s_waitcnt vmcnt(3)
; __device__ __forceinline__ float bflo(unsigned u) { return __uint_as_float(u << 16); }
; __device__ __forceinline__ float bfhi(unsigned u) { return __uint_as_float(u & 0xFFFF0000u); }
; __device__ __forceinline__ float siluf_(float x) { return x * __builtin_amdgcn_rcpf(1.f + __expf(-x)); }
; __device__ __forceinline__ void ssd_pass2(const Params& p, int layer, int task, char* sm) {
;     ...
;       const int lp = 32 * wr + r32; const int l = 64 * lh + lp; const size_t tok = tok0 + l;
;       const float eo = __expf(sAcs[l * 8 + hh]);
;       float ss = 0.f;
; #pragma unroll
;       for (int q = 0; q < 4; q++) {
;         const int pp = 32 * wc2 + 8 * q + 4 * h5;
;         uint2 zz = *(const uint2*)(p.P + tok * PW + C_SSZ + hd * 64 + pp);
;         float v0 = (yd[4 * q] + eo * yo[4 * q]) * siluf_(bflo(zz.x));
;         float v1 = (yd[4 * q + 1] + eo * yo[4 * q + 1]) * siluf_(bfhi(zz.x));
;         float v2 = (yd[4 * q + 2] + eo * yo[4 * q + 2]) * siluf_(bflo(zz.y));
;         float v3 = (yd[4 * q + 3] + eo * yo[4 * q + 3]) * siluf_(bfhi(zz.y));
;         ss += v0 * v0 + v1 * v1 + v2 * v2 + v3 * v3;
;         *(uint2*)(p.Y + tok * YW + Y_SSD + hd * 64 + pp) = make_uint2(pk2(v0, v1), pk2(v2, v3));
;       }
;       sSsq[lp * 32 + hh * 4 + wc2 * 2 + h5] = ss;
;     }
	s_nop 3
	v_mov_b32_e32 v34, v60
	v_mov_b32_e32 v35, v61
	v_lshlrev_b32_e32 v52, 16, v34
	v_and_b32_e32 v53, 0xffff0000, v34
	v_mul_f32_e32 v34, 0xbfb8aa3b, v52
	v_exp_f32_e32 v34, v34
	s_nop 0
	v_add_f32_e32 v34, 1.0, v34
	v_rcp_f32_e32 v54, v34
	v_mul_f32_e32 v34, 0xbfb8aa3b, v53
	v_exp_f32_e32 v34, v34
	s_nop 0
	v_add_f32_e32 v34, 1.0, v34
	v_rcp_f32_e32 v55, v34
	v_lshlrev_b32_e32 v34, 16, v35
	v_and_b32_e32 v35, 0xffff0000, v35
	v_pk_mul_f32 v[36:37], v[54:55], v[52:53]
	s_nop 0
	v_pk_mul_f32 v[20:21], v[20:21], v[36:37]
	v_mul_f32_e32 v36, 0xbfb8aa3b, v34
	v_mul_f32_e32 v37, 0xbfb8aa3b, v35
	v_exp_f32_e32 v36, v36
	v_exp_f32_e32 v37, v37
	v_add_f32_e32 v36, 1.0, v36
	v_add_f32_e32 v37, 1.0, v37
	v_rcp_f32_e32 v36, v36
	v_rcp_f32_e32 v37, v37
	s_nop 0
	v_pk_mul_f32 v[34:35], v[36:37], v[34:35]
	s_nop 0
	v_pk_mul_f32 v[22:23], v[22:23], v[34:35]
	v_mov_b32_e32 v34, v16
	v_mov_b32_e32 v16, v17
	v_mov_b32_e32 v17, v21
	v_mov_b32_e32 v35, v20
	v_pk_mul_f32 v[16:17], v[16:17], v[16:17]
	s_nop 0
	v_pk_fma_f32 v[16:17], v[34:35], v[34:35], v[16:17]
	v_mov_b32_e32 v34, v18
	v_mov_b32_e32 v35, v22
	v_pk_fma_f32 v[16:17], v[34:35], v[34:35], v[16:17]
	v_mov_b32_e32 v18, v19
	v_mov_b32_e32 v19, v23
	v_pk_fma_f32 v[16:17], v[18:19], v[18:19], v[16:17]
	v_cvt_pk_bf16_f32 v18, v20, v21
	v_cvt_pk_bf16_f32 v19, v22, v23
	global_store_dwordx2 v[32:33], v[18:19], off offset:2064
	v_add_f32_e32 v16, v16, v17
	s_waitcnt vmcnt(3)
	s_nop 3
	v_mov_b32_e32 v18, v68
	v_mov_b32_e32 v19, v69
	v_lshlrev_b32_e32 v20, 16, v18
	v_and_b32_e32 v21, 0xffff0000, v18
	v_mul_f32_e32 v18, 0xbfb8aa3b, v20
	v_exp_f32_e32 v18, v18
	s_nop 0
	v_add_f32_e32 v18, 1.0, v18
	v_rcp_f32_e32 v22, v18
	v_mul_f32_e32 v18, 0xbfb8aa3b, v21
	v_exp_f32_e32 v18, v18
	s_nop 0
	v_add_f32_e32 v18, 1.0, v18
	v_rcp_f32_e32 v23, v18
	v_lshlrev_b32_e32 v18, 16, v19
	v_and_b32_e32 v19, 0xffff0000, v19
	v_pk_mul_f32 v[20:21], v[22:23], v[20:21]
	v_mul_f32_e32 v22, 0xbfb8aa3b, v18
	v_mul_f32_e32 v23, 0xbfb8aa3b, v19
	v_exp_f32_e32 v22, v22
	v_exp_f32_e32 v23, v23
	v_pk_mul_f32 v[20:21], v[24:25], v[20:21]
	v_pk_fma_f32 v[24:25], v[26:27], v[48:49], v[42:43] op_sel_hi:[1,0,1]
	v_add_f32_e32 v22, 1.0, v22
	v_add_f32_e32 v23, 1.0, v23
	v_rcp_f32_e32 v22, v22
	v_rcp_f32_e32 v23, v23
	s_nop 0
	v_pk_mul_f32 v[18:19], v[22:23], v[18:19]
	s_nop 0
	v_pk_mul_f32 v[18:19], v[24:25], v[18:19]
	v_cvt_pk_bf16_f32 v22, v20, v21
	v_cvt_pk_bf16_f32 v23, v18, v19
	global_store_dwordx2 v[32:33], v[22:23], off offset:2080
	s_waitcnt vmcnt(3)
	s_nop 3
	v_mov_b32_e32 v22, v76
	v_mov_b32_e32 v23, v77
	v_lshlrev_b32_e32 v24, 16, v22
	v_and_b32_e32 v25, 0xffff0000, v22
	v_mul_f32_e32 v22, 0xbfb8aa3b, v24
	v_exp_f32_e32 v22, v22
	s_nop 0
	v_add_f32_e32 v22, 1.0, v22
	v_rcp_f32_e32 v26, v22
	v_mul_f32_e32 v22, 0xbfb8aa3b, v25
	v_exp_f32_e32 v22, v22
	s_nop 0
	v_add_f32_e32 v22, 1.0, v22
	v_rcp_f32_e32 v27, v22
	v_lshlrev_b32_e32 v22, 16, v23
	v_and_b32_e32 v23, 0xffff0000, v23
	v_pk_mul_f32 v[24:25], v[26:27], v[24:25]
	v_mul_f32_e32 v26, 0xbfb8aa3b, v22
	v_mul_f32_e32 v27, 0xbfb8aa3b, v23
	v_exp_f32_e32 v26, v26
	v_exp_f32_e32 v27, v27
	v_pk_mul_f32 v[24:25], v[28:29], v[24:25]
	v_pk_fma_f32 v[28:29], v[30:31], v[48:49], v[46:47] op_sel_hi:[1,0,1]
	v_add_f32_e32 v26, 1.0, v26
	v_add_f32_e32 v27, 1.0, v27
	v_rcp_f32_e32 v26, v26
	v_rcp_f32_e32 v27, v27
	s_nop 0
	v_pk_mul_f32 v[22:23], v[26:27], v[22:23]
	v_mov_b32_e32 v26, v20
	v_mov_b32_e32 v20, v21
	v_mov_b32_e32 v21, v25
	v_pk_mul_f32 v[22:23], v[28:29], v[22:23]
	v_mov_b32_e32 v27, v24
	v_pk_mul_f32 v[20:21], v[20:21], v[20:21]
	v_cvt_pk_bf16_f32 v17, v22, v23
	v_pk_fma_f32 v[20:21], v[26:27], v[26:27], v[20:21]
	v_mov_b32_e32 v26, v18
	v_mov_b32_e32 v27, v22
	v_pk_fma_f32 v[20:21], v[26:27], v[26:27], v[20:21]
	v_mov_b32_e32 v18, v19
	v_mov_b32_e32 v19, v23
	v_pk_fma_f32 v[18:19], v[18:19], v[18:19], v[20:21]
	s_nop 0
	v_add_f32_e32 v16, v16, v18
	v_add_f32_e32 v18, v16, v19
	v_cvt_pk_bf16_f32 v16, v24, v25
	global_store_dwordx2 v[32:33], v[16:17], off offset:2096
	v_lshl_add_u32 v16, s78, 4, v247
	s_add_i32 s78, s78, 1
	s_cmp_eq_u32 s78, 8
	ds_write_b32 v16, v18 offset:60416
	s_cbranch_scc0 .LBB0_1623
	s_branch .LBB0_1784

; __device__ __forceinline__ float bflo(unsigned u) { return __uint_as_float(u << 16); }
; __device__ __forceinline__ float bfhi(unsigned u) { return __uint_as_float(u & 0xFFFF0000u); }
; __device__ __forceinline__ float siluf_(float x) { return x * __builtin_amdgcn_rcpf(1.f + __expf(-x)); }
; __device__ __forceinline__ f32x16 mfma32(bf16x8 a, bf16x8 b, f32x16 c) { return __builtin_amdgcn_mfma_f32_32x32x16_bf16(a, b, c, 0, 0, 0); }
; __device__ __forceinline__ void ssd_pass2(const Params& p, int layer, int task, char* sm) {
;     ...
;     for (int ks = 0; ks < nks; ks++) {
;       bf16x8 xf = *(const bf16x8*)(sXT + (32 * wc2 + r32) * 136 + ks * 16 + 8 * h5);
;       bf16x8 mf = *(const bf16x8*)(sM + (32 * wr + r32) * 136 + ks * 16 + 8 * h5);
;       yd = mfma32(xf, mf, yd);
;     }
;     {
; #pragma unroll
;       for (int ks = 0; ks < 8; ks++) {
;         bf16x8 cf = *(const bf16x8*)(sC + (32 * wr + r32) * 136 + ks * 16 + 8 * h5);
;         yo = mfma32(pfr[ks], cf, yo);
;       }
;     }
;     {
;       const int lp = 32 * wr + r32; const int l = 64 * lh + lp; const size_t tok = tok0 + l;
;       const float eo = __expf(sAcs[l * 8 + hh]);
;       float ss = 0.f;
; #pragma unroll
;       for (int q = 0; q < 4; q++) {
;         const int pp = 32 * wc2 + 8 * q + 4 * h5;
;         uint2 zz = *(const uint2*)(p.P + tok * PW + C_SSZ + hd * 64 + pp);
;         float v0 = (yd[4 * q] + eo * yo[4 * q]) * siluf_(bflo(zz.x));
;         float v1 = (yd[4 * q + 1] + eo * yo[4 * q + 1]) * siluf_(bfhi(zz.x));
;         float v2 = (yd[4 * q + 2] + eo * yo[4 * q + 2]) * siluf_(bflo(zz.y));
;         float v3 = (yd[4 * q + 3] + eo * yo[4 * q + 3]) * siluf_(bfhi(zz.y));
;         ss += v0 * v0 + v1 * v1 + v2 * v2 + v3 * v3;
;         *(uint2*)(p.Y + tok * YW + Y_SSD + hd * 64 + pp) = make_uint2(pk2(v0, v1), pk2(v2, v3));
;       }
.LBB0_2024:
	ds_read_b128 v[162:165], v144
	ds_read_b128 v[166:169], v160
	s_add_i32 s78, s78, 1
	v_add_u32_e32 v160, 32, v160
	s_cmp_ge_u32 s78, s85
	v_add_u32_e32 v144, 32, v144
	s_waitcnt lgkmcnt(0)
	v_mfma_f32_32x32x16_bf16 v[32:47], v[162:165], v[166:169], v[32:47]
	s_cbranch_scc0 .LBB0_2024
	v_cvt_pk_bf16_f32 v108, v108, v109
	v_cvt_pk_bf16_f32 v109, v110, v111
	v_cvt_pk_bf16_f32 v110, v100, v101
	v_cvt_pk_bf16_f32 v111, v102, v103
	v_cvt_pk_bf16_f32 v103, v94, v95
	v_cvt_pk_bf16_f32 v95, v86, v87
	v_cvt_pk_bf16_f32 v87, v78, v79
	v_cvt_pk_bf16_f32 v79, v70, v71
	v_cvt_pk_bf16_f32 v71, v62, v63
	v_cvt_pk_bf16_f32 v62, v52, v53
	v_cvt_pk_bf16_f32 v63, v54, v55
	v_cvt_pk_bf16_f32 v52, v56, v57
	v_cvt_pk_bf16_f32 v53, v58, v59
	v_cvt_pk_bf16_f32 v54, v48, v49
	v_cvt_pk_bf16_f32 v55, v50, v51
	ds_read_b128 v[48:51], v188 offset:8192
	ds_read_b128 v[56:59], v188 offset:8224
	s_waitcnt lgkmcnt(1)
	v_mfma_f32_32x32x16_bf16 v[16:31], v[108:111], v[48:51], v[16:31]
	v_cvt_pk_bf16_f32 v100, v104, v105
	v_cvt_pk_bf16_f32 v101, v106, v107
	v_cvt_pk_bf16_f32 v102, v92, v93
	v_cvt_pk_bf16_f32 v92, v96, v97
	v_cvt_pk_bf16_f32 v93, v98, v99
	v_cvt_pk_bf16_f32 v94, v84, v85
	ds_read_b128 v[48:51], v188 offset:8256
	s_waitcnt lgkmcnt(1)
	v_mfma_f32_32x32x16_bf16 v[16:31], v[100:103], v[56:59], v[16:31]
	v_cvt_pk_bf16_f32 v84, v88, v89
	v_cvt_pk_bf16_f32 v85, v90, v91
	v_cvt_pk_bf16_f32 v86, v76, v77
	v_cvt_pk_bf16_f32 v76, v80, v81
	v_cvt_pk_bf16_f32 v77, v82, v83
	v_cvt_pk_bf16_f32 v78, v68, v69
	v_cvt_pk_bf16_f32 v68, v72, v73
	s_waitcnt lgkmcnt(0)
	v_mfma_f32_32x32x16_bf16 v[16:31], v[92:95], v[48:51], v[16:31]
	ds_read_b128 v[48:51], v188 offset:8288
	v_cvt_pk_bf16_f32 v69, v74, v75
	v_cvt_pk_bf16_f32 v70, v60, v61
	v_cvt_pk_bf16_f32 v60, v64, v65
	v_cvt_pk_bf16_f32 v61, v66, v67
	s_lshl_b32 s68, s68, 1
	s_waitcnt lgkmcnt(0)
	v_mfma_f32_32x32x16_bf16 v[16:31], v[84:87], v[48:51], v[16:31]
	ds_read_b128 v[48:51], v188 offset:8320
	s_waitcnt lgkmcnt(0)
	v_mfma_f32_32x32x16_bf16 v[16:31], v[76:79], v[48:51], v[16:31]
	ds_read_b128 v[48:51], v188 offset:8352
	s_waitcnt lgkmcnt(0)
	v_mfma_f32_32x32x16_bf16 v[16:31], v[68:71], v[48:51], v[16:31]
	ds_read_b128 v[48:51], v188 offset:8384
	s_waitcnt lgkmcnt(0)
	v_mfma_f32_32x32x16_bf16 v[16:31], v[60:63], v[48:51], v[16:31]
	ds_read_b128 v[48:51], v188 offset:8416
	s_waitcnt lgkmcnt(0)
	v_mfma_f32_32x32x16_bf16 v[16:31], v[52:55], v[48:51], v[16:31]
	v_lshl_add_u64 v[50:51], v[156:157], 0, s[68:69]
	global_load_dwordx2 v[52:53], v[50:51], off
	global_load_dwordx2 v[60:61], v[50:51], off offset:16
	global_load_dwordx2 v[68:69], v[50:51], off offset:32
	global_load_dwordx2 v[76:77], v[50:51], off offset:48
	v_lshl_add_u32 v48, s86, 2, v246
	ds_read_b32 v48, v48
	s_waitcnt lgkmcnt(0)
	v_mul_f32_e32 v48, 0x3fb8aa3b, v48
	v_exp_f32_e32 v48, v48
	s_waitcnt vmcnt(3)
	v_lshlrev_b32_e32 v54, 16, v52
	v_mul_f32_e32 v49, 0xbfb8aa3b, v54
	v_exp_f32_e32 v49, v49
	v_and_b32_e32 v55, 0xffff0000, v52
	v_add_f32_e32 v49, 1.0, v49
	v_pk_fma_f32 v[16:17], v[16:17], v[48:49], v[32:33] op_sel_hi:[1,0,1]
	v_mul_f32_e32 v32, 0xbfb8aa3b, v55
	v_exp_f32_e32 v32, v32
	v_rcp_f32_e32 v56, v49
	v_add_f32_e32 v32, 1.0, v32
	v_rcp_f32_e32 v57, v32
	s_nop 0
	v_pk_mul_f32 v[32:33], v[56:57], v[54:55]
	s_nop 0
	v_pk_mul_f32 v[16:17], v[16:17], v[32:33]
	v_lshlrev_b32_e32 v32, 16, v53
	v_mul_f32_e32 v49, 0xbfb8aa3b, v32
	v_exp_f32_e32 v49, v49
	v_and_b32_e32 v33, 0xffff0000, v53
	v_add_f32_e32 v49, 1.0, v49
	v_pk_fma_f32 v[18:19], v[18:19], v[48:49], v[34:35] op_sel_hi:[1,0,1]
	v_mul_f32_e32 v34, 0xbfb8aa3b, v33
	v_exp_f32_e32 v34, v34
	v_rcp_f32_e32 v52, v49
	v_pk_fma_f32 v[20:21], v[20:21], v[48:49], v[36:37] op_sel_hi:[1,0,1]
	v_pk_fma_f32 v[22:23], v[22:23], v[48:49], v[38:39] op_sel_hi:[1,0,1]
	v_add_f32_e32 v34, 1.0, v34
	v_rcp_f32_e32 v53, v34
	v_cvt_pk_bf16_f32 v34, v16, v17
	v_pk_fma_f32 v[24:25], v[24:25], v[48:49], v[40:41] op_sel_hi:[1,0,1]
	v_pk_fma_f32 v[28:29], v[28:29], v[48:49], v[44:45] op_sel_hi:[1,0,1]
	v_pk_mul_f32 v[32:33], v[52:53], v[32:33]
	s_nop 0
	v_pk_mul_f32 v[18:19], v[18:19], v[32:33]
	v_lshl_add_u64 v[32:33], v[158:159], 0, s[68:69]
	v_cvt_pk_bf16_f32 v35, v18, v19
	global_store_dwordx2 v[32:33], v[34:35], off offset:2048
	s_waitcnt vmcnt(3)
; __device__ __forceinline__ float bflo(unsigned u) { return __uint_as_float(u << 16); }
; __device__ __forceinline__ float bfhi(unsigned u) { return __uint_as_float(u & 0xFFFF0000u); }
; __device__ __forceinline__ float siluf_(float x) { return x * __builtin_amdgcn_rcpf(1.f + __expf(-x)); }
; __device__ __forceinline__ void ssd_pass2(const Params& p, int layer, int task, char* sm) {
;     ...
;       const int lp = 32 * wr + r32; const int l = 64 * lh + lp; const size_t tok = tok0 + l;
;       const float eo = __expf(sAcs[l * 8 + hh]);
;       float ss = 0.f;
; #pragma unroll
;       for (int q = 0; q < 4; q++) {
;         const int pp = 32 * wc2 + 8 * q + 4 * h5;
;         uint2 zz = *(const uint2*)(p.P + tok * PW + C_SSZ + hd * 64 + pp);
;         float v0 = (yd[4 * q] + eo * yo[4 * q]) * siluf_(bflo(zz.x));
;         float v1 = (yd[4 * q + 1] + eo * yo[4 * q + 1]) * siluf_(bfhi(zz.x));
;         float v2 = (yd[4 * q + 2] + eo * yo[4 * q + 2]) * siluf_(bflo(zz.y));
;         float v3 = (yd[4 * q + 3] + eo * yo[4 * q + 3]) * siluf_(bfhi(zz.y));
;         ss += v0 * v0 + v1 * v1 + v2 * v2 + v3 * v3;
;         *(uint2*)(p.Y + tok * YW + Y_SSD + hd * 64 + pp) = make_uint2(pk2(v0, v1), pk2(v2, v3));
;       }
;       sSsq[lp * 32 + hh * 4 + wc2 * 2 + h5] = ss;
;     }
	s_nop 3
	v_mov_b32_e32 v34, v60
	v_mov_b32_e32 v35, v61
	v_lshlrev_b32_e32 v52, 16, v34
	v_and_b32_e32 v53, 0xffff0000, v34
	v_mul_f32_e32 v34, 0xbfb8aa3b, v52
	v_exp_f32_e32 v34, v34
	s_nop 0
	v_add_f32_e32 v34, 1.0, v34
	v_rcp_f32_e32 v54, v34
	v_mul_f32_e32 v34, 0xbfb8aa3b, v53
	v_exp_f32_e32 v34, v34
	s_nop 0
	v_add_f32_e32 v34, 1.0, v34
	v_rcp_f32_e32 v55, v34
	v_lshlrev_b32_e32 v34, 16, v35
	v_and_b32_e32 v35, 0xffff0000, v35
	v_pk_mul_f32 v[36:37], v[54:55], v[52:53]
	s_nop 0
	v_pk_mul_f32 v[20:21], v[20:21], v[36:37]
	v_mul_f32_e32 v36, 0xbfb8aa3b, v34
	v_mul_f32_e32 v37, 0xbfb8aa3b, v35
	v_exp_f32_e32 v36, v36
	v_exp_f32_e32 v37, v37
	v_add_f32_e32 v36, 1.0, v36
	v_add_f32_e32 v37, 1.0, v37
	v_rcp_f32_e32 v36, v36
	v_rcp_f32_e32 v37, v37
	s_nop 0
	v_pk_mul_f32 v[34:35], v[36:37], v[34:35]
	s_nop 0
	v_pk_mul_f32 v[22:23], v[22:23], v[34:35]
	v_mov_b32_e32 v34, v16
	v_mov_b32_e32 v16, v17
	v_mov_b32_e32 v17, v21
	v_mov_b32_e32 v35, v20
	v_pk_mul_f32 v[16:17], v[16:17], v[16:17]
	s_nop 0
	v_pk_fma_f32 v[16:17], v[34:35], v[34:35], v[16:17]
	v_mov_b32_e32 v34, v18
	v_mov_b32_e32 v35, v22
	v_pk_fma_f32 v[16:17], v[34:35], v[34:35], v[16:17]
	v_mov_b32_e32 v18, v19
	v_mov_b32_e32 v19, v23
	v_pk_fma_f32 v[16:17], v[18:19], v[18:19], v[16:17]
	v_cvt_pk_bf16_f32 v18, v20, v21
	v_cvt_pk_bf16_f32 v19, v22, v23
	global_store_dwordx2 v[32:33], v[18:19], off offset:2064
	v_add_f32_e32 v16, v16, v17
	s_waitcnt vmcnt(3)
	s_nop 3
	v_mov_b32_e32 v18, v68
	v_mov_b32_e32 v19, v69
	v_lshlrev_b32_e32 v20, 16, v18
	v_and_b32_e32 v21, 0xffff0000, v18
	v_mul_f32_e32 v18, 0xbfb8aa3b, v20
	v_exp_f32_e32 v18, v18
	s_nop 0
	v_add_f32_e32 v18, 1.0, v18
	v_rcp_f32_e32 v22, v18
	v_mul_f32_e32 v18, 0xbfb8aa3b, v21
	v_exp_f32_e32 v18, v18
	s_nop 0
	v_add_f32_e32 v18, 1.0, v18
	v_rcp_f32_e32 v23, v18
	v_lshlrev_b32_e32 v18, 16, v19
	v_and_b32_e32 v19, 0xffff0000, v19
	v_pk_mul_f32 v[20:21], v[22:23], v[20:21]
	v_mul_f32_e32 v22, 0xbfb8aa3b, v18
	v_mul_f32_e32 v23, 0xbfb8aa3b, v19
	v_exp_f32_e32 v22, v22
	v_exp_f32_e32 v23, v23
	v_pk_mul_f32 v[20:21], v[24:25], v[20:21]
	v_pk_fma_f32 v[24:25], v[26:27], v[48:49], v[42:43] op_sel_hi:[1,0,1]
	v_add_f32_e32 v22, 1.0, v22
	v_add_f32_e32 v23, 1.0, v23
	v_rcp_f32_e32 v22, v22
	v_rcp_f32_e32 v23, v23
	s_nop 0
	v_pk_mul_f32 v[18:19], v[22:23], v[18:19]
	s_nop 0
	v_pk_mul_f32 v[18:19], v[24:25], v[18:19]
	v_cvt_pk_bf16_f32 v22, v20, v21
	v_cvt_pk_bf16_f32 v23, v18, v19
	global_store_dwordx2 v[32:33], v[22:23], off offset:2080
	s_waitcnt vmcnt(3)
	s_nop 3
	v_mov_b32_e32 v22, v76
	v_mov_b32_e32 v23, v77
	v_lshlrev_b32_e32 v24, 16, v22
	v_and_b32_e32 v25, 0xffff0000, v22
	v_mul_f32_e32 v22, 0xbfb8aa3b, v24
	v_exp_f32_e32 v22, v22
	s_nop 0
	v_add_f32_e32 v22, 1.0, v22
	v_rcp_f32_e32 v26, v22
	v_mul_f32_e32 v22, 0xbfb8aa3b, v25
	v_exp_f32_e32 v22, v22
	s_nop 0
	v_add_f32_e32 v22, 1.0, v22
	v_rcp_f32_e32 v27, v22
	v_lshlrev_b32_e32 v22, 16, v23
	v_and_b32_e32 v23, 0xffff0000, v23
	v_pk_mul_f32 v[24:25], v[26:27], v[24:25]
	v_mul_f32_e32 v26, 0xbfb8aa3b, v22
	v_mul_f32_e32 v27, 0xbfb8aa3b, v23
	v_exp_f32_e32 v26, v26
	v_exp_f32_e32 v27, v27
	v_pk_mul_f32 v[24:25], v[28:29], v[24:25]
	v_pk_fma_f32 v[28:29], v[30:31], v[48:49], v[46:47] op_sel_hi:[1,0,1]
	v_add_f32_e32 v26, 1.0, v26
	v_add_f32_e32 v27, 1.0, v27
	v_rcp_f32_e32 v26, v26
	v_rcp_f32_e32 v27, v27
	s_nop 0
	v_pk_mul_f32 v[22:23], v[26:27], v[22:23]
	v_mov_b32_e32 v26, v20
	v_mov_b32_e32 v20, v21
	v_mov_b32_e32 v21, v25
	v_pk_mul_f32 v[22:23], v[28:29], v[22:23]
	v_mov_b32_e32 v27, v24
	v_pk_mul_f32 v[20:21], v[20:21], v[20:21]
	v_cvt_pk_bf16_f32 v17, v22, v23
	v_pk_fma_f32 v[20:21], v[26:27], v[26:27], v[20:21]
	v_mov_b32_e32 v26, v18
	v_mov_b32_e32 v27, v22
	v_pk_fma_f32 v[20:21], v[26:27], v[26:27], v[20:21]
	v_mov_b32_e32 v18, v19
	v_mov_b32_e32 v19, v23
	v_pk_fma_f32 v[18:19], v[18:19], v[18:19], v[20:21]
	s_nop 0
	v_add_f32_e32 v16, v16, v18
	v_add_f32_e32 v18, v16, v19
	v_cvt_pk_bf16_f32 v16, v24, v25
	global_store_dwordx2 v[32:33], v[16:17], off offset:2096
	v_lshl_add_u32 v16, s86, 4, v247
	s_add_i32 s86, s86, 1
	s_cmp_eq_u32 s86, 8
	ds_write_b32 v16, v18 offset:60416
	s_cbranch_scc0 .LBB0_1872
	s_branch .LBB0_2033
